# ple K-loops: steady-state scalar-base DMA (saddr form)
# speedup vs baseline: 1.0169x; 1.0015x over previous
; #define MFMA16(a, b, c) __builtin_amdgcn_mfma_f32_16x16x32_bf16((a), (b), (c), 0, 0, 0)
; template <int MF, int NF, bool SWAP = true>
; DI void gemm_main(f32x4 (&acc)[MF][NF], const u16* __restrict__ Ab, int lda, const u16* __restrict__ Bb, int ldb,
;                   int K, char* shm) {
;     ...
;   const int a_off = lds_byte<2>(fr, fq * 8) + wr * (MF * 2048);
;   const int b_off = lds_byte<2>(fr, fq * 8) + wc * (NF * 2048);
;   G_STAGE(0, 0);
;   if constexpr (RING3) {
;     if (nt > 1) { G_STAGE(1, 1); asm volatile("s_waitcnt vmcnt(6)" ::: "memory"); }
;     else asm volatile("s_waitcnt vmcnt(0)" ::: "memory");
;     asm volatile("s_waitcnt lgkmcnt(0)" ::: "memory");
;     __builtin_amdgcn_s_barrier();
;   } else {
;     asm volatile("s_waitcnt vmcnt(0)" ::: "memory");
;     __syncthreads();
;   }
;   int cur3 = 0, nxt3 = 2;
; #pragma clang loop unroll(disable)
;   for (int t = 0; t < nt; ++t) {
;     const int cur = RING3 ? cur3 : (t & 1);
;     if constexpr (RING3) {
;       if (t + 2 < nt) G_STAGE(nxt3, t + 2);
;     } else {
;       if (t + 1 < nt) G_STAGE(cur ^ 1, t + 1);
;     }
;     const char* sA = shm + cur * STAGE;
;     const char* sB = sA + TILE_A;
;     ...
;     for (int ks = 0; ks < 2; ++ks) {
;       bf16x8 Bf[NF];
; #pragma unroll
;       for (int n = 0; n < NF; ++n) Bf[n] = *(const bf16x8*)(sB + b_off + n * 2048 + ks * 1024);
;       constexpr int MG = (NF == 2 && MF == 8) ? 4 : MF;
; #pragma unroll
;       for (int mg = 0; mg < MF / MG; ++mg) {
;         bf16x8 At[MG];
; #pragma unroll
;         for (int m = 0; m < MG; ++m) At[m] = *(const bf16x8*)(sA + a_off + (mg * MG + m) * 2048 + ks * 1024);
; #pragma unroll
;         for (int m = 0; m < MG; ++m)
; #pragma unroll
;           for (int n = 0; n < NF; ++n)
;             acc[mg * MG + m][n] = SWAP ? MFMA16(Bf[n], At[m], acc[mg * MG + m][n]) : MFMA16(At[m], Bf[n], acc[mg * MG + m][n]);
;         if (mg == 0) __builtin_amdgcn_sched_group_barrier(0x100, MG + NF, 0);
;         else __builtin_amdgcn_sched_group_barrier(0x100, MG, 0);
;         __builtin_amdgcn_sched_group_barrier(0x008, MG * NF, 0);
.LBB0_920:
	s_mul_i32 s29, s28, 0xc000
	v_or_b32_e32 v69, s29, v66
	v_add_u32_e32 v94, v69, v67
	v_add_u32_e32 v69, v69, v65
	ds_read_b128 v[70:73], v94 offset:32768
	ds_read_b128 v[74:77], v94 offset:34816
	ds_read_b128 v[78:81], v69
	ds_read_b128 v[82:85], v69 offset:2048
	ds_read_b128 v[86:89], v69 offset:4096
	ds_read_b128 v[90:93], v69 offset:6144
	ds_read_b128 v[96:99], v69 offset:8192
	ds_read_b128 v[100:103], v69 offset:10240
	ds_read_b128 v[104:107], v69 offset:12288
	ds_read_b128 v[108:111], v69 offset:14336
	s_cmp_gt_u32 s27, 1
	s_cselect_b64 s[12:13], -1, 0
	s_and_b64 vcc, exec, s[12:13]
	s_cbranch_vccnz .Lppa_nodma
	s_cmp_eq_u32 s27, 0
	s_cbranch_scc1 .Lppa_first
	v_mfma_f32_16x16x32_bf16 v[60:63], v[112:115], v[120:123], v[60:63]
	s_mul_i32 s14, s26, 0xc000
	v_add_u32_e32 v129, s14, v64
	v_mfma_f32_16x16x32_bf16 v[56:59], v[116:119], v[120:123], v[56:59]
	s_nop 0
	v_readfirstlane_b32 s14, v129
	s_nop 1
	s_add_u32 m0, s14, 0x0
	v_mfma_f32_16x16x32_bf16 v[52:55], v[112:115], v[124:127], v[52:55]
	global_load_lds_dwordx4 v246, s[98:99]
	s_add_u32 m0, s14, 0x2000
	v_mfma_f32_16x16x32_bf16 v[48:51], v[116:119], v[124:127], v[48:51]
	global_load_lds_dwordx4 v247, s[98:99]
	s_add_u32 m0, s14, 0x4000
	v_mfma_f32_16x16x32_bf16 v[44:47], v[112:115], v[136:139], v[44:47]
	global_load_lds_dwordx4 v248, s[98:99]
	s_add_u32 m0, s14, 0x6000
	v_mfma_f32_16x16x32_bf16 v[40:43], v[116:119], v[136:139], v[40:43]
	global_load_lds_dwordx4 v249, s[98:99]
	s_add_u32 m0, s14, 0x8000
	v_mfma_f32_16x16x32_bf16 v[36:39], v[112:115], v[140:143], v[36:39]
	global_load_lds_dwordx4 v246, s[100:101]
	s_add_u32 m0, s14, 0xa000
	v_mfma_f32_16x16x32_bf16 v[32:35], v[116:119], v[140:143], v[32:35]
	global_load_lds_dwordx4 v247, s[100:101]
	v_mfma_f32_16x16x32_bf16 v[28:31], v[112:115], v[144:147], v[28:31]
	s_add_u32 s98, s98, 0x80
	s_addc_u32 s99, s99, 0
	s_add_u32 s100, s100, 0x80
	s_addc_u32 s101, s101, 0
	v_mfma_f32_16x16x32_bf16 v[24:27], v[116:119], v[144:147], v[24:27]
	v_mfma_f32_16x16x32_bf16 v[20:23], v[112:115], v[148:151], v[20:23]
	v_mfma_f32_16x16x32_bf16 v[16:19], v[116:119], v[148:151], v[16:19]
	v_mfma_f32_16x16x32_bf16 v[12:15], v[112:115], v[152:155], v[12:15]
	v_mfma_f32_16x16x32_bf16 v[8:11], v[116:119], v[152:155], v[8:11]
	v_mfma_f32_16x16x32_bf16 v[4:7], v[112:115], v[156:159], v[4:7]
	v_mfma_f32_16x16x32_bf16 v[0:3], v[116:119], v[156:159], v[0:3]
	s_branch .Lppa_main
.Lppa_first:
	v_add_u32_e32 v95, s25, v68
	s_mul_i32 s14, s26, 0xc000
	v_add_u32_e32 v130, 0x80, v95
	v_add_u32_e32 v129, s14, v64
	v_ashrrev_i32_e32 v131, 31, v130
	v_lshlrev_b64 v[130:131], 1, v[130:131]
	v_readfirstlane_b32 s14, v129
	v_lshl_add_u64 v[160:161], s[8:9], 0, v[130:131]
	v_subrev_u32_e32 v246, s8, v160
	s_mov_b32 m0, s14
	v_add_u32_e32 v132, 0x2000, v129
	global_load_lds_dwordx4 v[160:161], off
	v_add_u32_e32 v160, 0x4080, v95
	v_ashrrev_i32_e32 v161, 31, v160
	v_lshlrev_b64 v[160:161], 1, v[160:161]
	v_readfirstlane_b32 s14, v132
	v_lshl_add_u64 v[162:163], s[8:9], 0, v[160:161]
	v_subrev_u32_e32 v247, s8, v162
	s_mov_b32 m0, s14
	v_add_u32_e32 v132, 0x4000, v129
	global_load_lds_dwordx4 v[162:163], off
	v_add_u32_e32 v162, 0x8080, v95
	v_ashrrev_i32_e32 v163, 31, v162
	v_readfirstlane_b32 s14, v132
	v_lshl_add_u64 v[162:163], v[162:163], 1, s[8:9]
	v_subrev_u32_e32 v248, s8, v162
	s_mov_b32 m0, s14
	v_lshl_add_u64 v[130:131], s[10:11], 0, v[130:131]
	global_load_lds_dwordx4 v[162:163], off
	v_add_u32_e32 v162, 0xc080, v95
	v_add_u32_e32 v95, 0x6000, v129
	v_ashrrev_i32_e32 v163, 31, v162
	v_readfirstlane_b32 s14, v95
	v_lshl_add_u64 v[162:163], v[162:163], 1, s[8:9]
	v_subrev_u32_e32 v249, s8, v162
	s_mov_b32 m0, s14
	s_nop 0
	global_load_lds_dwordx4 v[162:163], off
	v_add_u32_e32 v162, 0x8000, v129
	v_add_u32_e32 v129, 0xa000, v129
	v_readfirstlane_b32 s14, v162
	s_mov_b32 m0, s14
	v_readfirstlane_b32 s14, v129
	global_load_lds_dwordx4 v[130:131], off
	v_lshl_add_u64 v[130:131], s[10:11], 0, v[160:161]
	s_mov_b32 m0, s14
	s_nop 0
	global_load_lds_dwordx4 v[130:131], off
	s_add_u32 s98, s8, 0x80
	s_addc_u32 s99, s9, 0
	s_add_u32 s100, s10, 0x80
	s_addc_u32 s101, s11, 0
	s_branch .Lppa_main

; #define MFMA16(a, b, c) __builtin_amdgcn_mfma_f32_16x16x32_bf16((a), (b), (c), 0, 0, 0)
; template <int MF, int NF, bool SWAP = true>
; DI void gemm_main(f32x4 (&acc)[MF][NF], const u16* __restrict__ Ab, int lda, const u16* __restrict__ Bb, int ldb,
;                   int K, char* shm) {
;     ...
;   const int a_off = lds_byte<2>(fr, fq * 8) + wr * (MF * 2048);
;   const int b_off = lds_byte<2>(fr, fq * 8) + wc * (NF * 2048);
;   G_STAGE(0, 0);
;   if constexpr (RING3) {
;     if (nt > 1) { G_STAGE(1, 1); asm volatile("s_waitcnt vmcnt(6)" ::: "memory"); }
;     else asm volatile("s_waitcnt vmcnt(0)" ::: "memory");
;     asm volatile("s_waitcnt lgkmcnt(0)" ::: "memory");
;     __builtin_amdgcn_s_barrier();
;   } else {
;     asm volatile("s_waitcnt vmcnt(0)" ::: "memory");
;     __syncthreads();
;   }
;   int cur3 = 0, nxt3 = 2;
; #pragma clang loop unroll(disable)
;   for (int t = 0; t < nt; ++t) {
;     const int cur = RING3 ? cur3 : (t & 1);
;     if constexpr (RING3) {
;       if (t + 2 < nt) G_STAGE(nxt3, t + 2);
;     } else {
;       if (t + 1 < nt) G_STAGE(cur ^ 1, t + 1);
;     }
;     const char* sA = shm + cur * STAGE;
;     const char* sB = sA + TILE_A;
;     ...
;     for (int ks = 0; ks < 2; ++ks) {
;       bf16x8 Bf[NF];
; #pragma unroll
;       for (int n = 0; n < NF; ++n) Bf[n] = *(const bf16x8*)(sB + b_off + n * 2048 + ks * 1024);
;       constexpr int MG = (NF == 2 && MF == 8) ? 4 : MF;
; #pragma unroll
;       for (int mg = 0; mg < MF / MG; ++mg) {
;         bf16x8 At[MG];
; #pragma unroll
;         for (int m = 0; m < MG; ++m) At[m] = *(const bf16x8*)(sA + a_off + (mg * MG + m) * 2048 + ks * 1024);
; #pragma unroll
;         for (int m = 0; m < MG; ++m)
; #pragma unroll
;           for (int n = 0; n < NF; ++n)
;             acc[mg * MG + m][n] = SWAP ? MFMA16(Bf[n], At[m], acc[mg * MG + m][n]) : MFMA16(At[m], Bf[n], acc[mg * MG + m][n]);
;         if (mg == 0) __builtin_amdgcn_sched_group_barrier(0x100, MG + NF, 0);
;         else __builtin_amdgcn_sched_group_barrier(0x100, MG, 0);
;         __builtin_amdgcn_sched_group_barrier(0x008, MG * NF, 0);
.LBB0_928:
	s_mul_i32 s29, s27, 0xc000
	v_or_b32_e32 v137, s29, v131
	v_add_u32_e32 v162, v137, v132
	v_add_u32_e32 v137, v137, v130
	ds_read_b128 v[138:141], v162 offset:32768
	ds_read_b128 v[142:145], v162 offset:34816
	ds_read_b128 v[146:149], v137
	ds_read_b128 v[150:153], v137 offset:2048
	ds_read_b128 v[154:157], v137 offset:4096
	ds_read_b128 v[158:161], v137 offset:6144
	ds_read_b128 v[164:167], v137 offset:8192
	ds_read_b128 v[168:171], v137 offset:10240
	ds_read_b128 v[172:175], v137 offset:12288
	ds_read_b128 v[176:179], v137 offset:14336
	s_cmp_gt_u32 s26, 13
	s_cselect_b64 s[12:13], -1, 0
	s_and_b64 vcc, exec, s[12:13]
	s_cbranch_vccnz .Lppb_nodma
	s_cmp_eq_u32 s26, 0
	s_cbranch_scc1 .Lppb_first
	v_mfma_f32_16x16x32_bf16 v[124:127], v[180:183], v[188:191], v[124:127]
	s_mul_i32 s14, s5, 0xc000
	v_add_u32_e32 v211, s14, v129
	v_mfma_f32_16x16x32_bf16 v[120:123], v[184:187], v[188:191], v[120:123]
	s_nop 0
	v_readfirstlane_b32 s14, v211
	s_nop 1
	s_add_u32 m0, s14, 0x0
	v_mfma_f32_16x16x32_bf16 v[116:119], v[180:183], v[192:195], v[116:119]
	global_load_lds_dwordx4 v246, s[98:99]
	s_add_u32 m0, s14, 0x2000
	v_mfma_f32_16x16x32_bf16 v[112:115], v[184:187], v[192:195], v[112:115]
	global_load_lds_dwordx4 v247, s[98:99]
	s_add_u32 m0, s14, 0x4000
	v_mfma_f32_16x16x32_bf16 v[108:111], v[180:183], v[196:199], v[108:111]
	global_load_lds_dwordx4 v248, s[98:99]
	s_add_u32 m0, s14, 0x6000
	v_mfma_f32_16x16x32_bf16 v[104:107], v[184:187], v[196:199], v[104:107]
	global_load_lds_dwordx4 v249, s[98:99]
	s_add_u32 m0, s14, 0x8000
	v_mfma_f32_16x16x32_bf16 v[100:103], v[180:183], v[212:215], v[100:103]
	global_load_lds_dwordx4 v246, s[100:101]
	s_add_u32 m0, s14, 0xa000
	v_mfma_f32_16x16x32_bf16 v[96:99], v[184:187], v[212:215], v[96:99]
	global_load_lds_dwordx4 v247, s[100:101]
	v_mfma_f32_16x16x32_bf16 v[92:95], v[180:183], v[216:219], v[92:95]
	s_add_u32 s98, s98, 0x80
	s_addc_u32 s99, s99, 0
	s_add_u32 s100, s100, 0x80
	s_addc_u32 s101, s101, 0
	v_mfma_f32_16x16x32_bf16 v[88:91], v[184:187], v[216:219], v[88:91]
	v_mfma_f32_16x16x32_bf16 v[84:87], v[180:183], v[220:223], v[84:87]
	v_mfma_f32_16x16x32_bf16 v[80:83], v[184:187], v[220:223], v[80:83]
	v_mfma_f32_16x16x32_bf16 v[76:79], v[180:183], v[224:227], v[76:79]
	v_mfma_f32_16x16x32_bf16 v[72:75], v[184:187], v[224:227], v[72:75]
	v_mfma_f32_16x16x32_bf16 v[68:71], v[180:183], v[228:231], v[68:71]
	v_mfma_f32_16x16x32_bf16 v[64:67], v[184:187], v[228:231], v[64:67]
	s_branch .Lppb_main
.Lppb_first:
	v_add_u32_e32 v163, s25, v136
	s_mul_i32 s14, s5, 0xc000
	v_add_u32_e32 v200, 0x80, v163
	v_add_u32_e32 v211, s14, v129
	v_ashrrev_i32_e32 v201, 31, v200
	v_lshlrev_b64 v[200:201], 1, v[200:201]
	v_readfirstlane_b32 s14, v211
	v_lshl_add_u64 v[232:233], s[8:9], 0, v[200:201]
	v_subrev_u32_e32 v246, s8, v232
	s_mov_b32 m0, s14
	v_add_u32_e32 v236, 0x2000, v211
	global_load_lds_dwordx4 v[232:233], off
	v_add_u32_e32 v232, 0x10080, v163
	v_ashrrev_i32_e32 v233, 31, v232
	v_lshlrev_b64 v[232:233], 1, v[232:233]
	v_readfirstlane_b32 s14, v236
	v_lshl_add_u64 v[234:235], s[8:9], 0, v[232:233]
	v_subrev_u32_e32 v247, s8, v234
	s_mov_b32 m0, s14
	v_add_u32_e32 v236, 0x4000, v211
	global_load_lds_dwordx4 v[234:235], off
	v_add_u32_e32 v234, 0x20080, v163
	v_ashrrev_i32_e32 v235, 31, v234
	v_readfirstlane_b32 s14, v236
	v_lshl_add_u64 v[234:235], v[234:235], 1, s[8:9]
	v_subrev_u32_e32 v248, s8, v234
	s_mov_b32 m0, s14
	v_lshl_add_u64 v[200:201], s[10:11], 0, v[200:201]
	global_load_lds_dwordx4 v[234:235], off
	v_add_u32_e32 v234, 0x30080, v163
	v_add_u32_e32 v163, 0x6000, v211
	v_ashrrev_i32_e32 v235, 31, v234
	v_readfirstlane_b32 s14, v163
	v_lshl_add_u64 v[234:235], v[234:235], 1, s[8:9]
	v_subrev_u32_e32 v249, s8, v234
	s_mov_b32 m0, s14
	s_nop 0
	global_load_lds_dwordx4 v[234:235], off
	v_add_u32_e32 v234, 0x8000, v211
	v_add_u32_e32 v211, 0xa000, v211
	v_readfirstlane_b32 s14, v234
	s_mov_b32 m0, s14
	v_readfirstlane_b32 s14, v211
	global_load_lds_dwordx4 v[200:201], off
	v_lshl_add_u64 v[200:201], s[10:11], 0, v[232:233]
	s_mov_b32 m0, s14
	s_nop 0
	global_load_lds_dwordx4 v[200:201], off
	s_add_u32 s98, s8, 0x80
	s_addc_u32 s99, s9, 0
	s_add_u32 s100, s10, 0x80
	s_addc_u32 s101, s11, 0
	s_branch .Lppb_main
